# weight-conversion transpose tiles: 13 of 16 masked row loads per thread issued as a batch with counted waits (was load-wait-write per row)
# baseline (speedup 1.0000x reference)
; DI void transpose_tile(const float* __restrict__ src, int sld, int k0, int n0, int kind, u16* __restrict__ dst, int dld,
;                        char* ldsraw) {
;     ...
; #pragma unroll
;     for (int i = 0; i < 16; ++i) {
;       const int kk = kq * 16 + i;
;       t[kk * 65 + nn] = (sc >= 0) ? src[(size_t)(k0 + kk) * sld + sc] : 0.f;
;     }
.LBB0_70:
	s_or_b64 exec, exec, s[0:1]
	v_and_b32_e32 v0, 63, v4
	v_lshlrev_b32_e32 v0, 2, v0
	v_mul_lo_u32 v7, v6, s57
	v_add_u32_e32 v7, v0, v7
	s_waitcnt vmcnt(0)
	ds_write_b32 v7, v9
	v_mov_b32_e32 v228, 0
	v_mov_b32_e32 v229, 0
	v_mov_b32_e32 v230, 0
	v_mov_b32_e32 v231, 0
	v_mov_b32_e32 v232, 0
	v_mov_b32_e32 v233, 0
	v_mov_b32_e32 v234, 0
	v_mov_b32_e32 v235, 0
	v_mov_b32_e32 v236, 0
	v_mov_b32_e32 v237, 0
	v_mov_b32_e32 v238, 0
	v_mov_b32_e32 v239, 0
	v_mov_b32_e32 v240, 0
	s_and_saveexec_b64 s[0:1], vcc
	s_cbranch_execz .Lbt_1
	v_add3_u32 v246, s2, v6, 1
	v_mad_i64_i32 v[246:247], s[10:11], v246, s58, v[2:3]
	global_load_dword v228, v[246:247], off
	v_add3_u32 v246, s2, v6, 2
	v_mad_i64_i32 v[246:247], s[10:11], v246, s58, v[2:3]
	global_load_dword v229, v[246:247], off
	v_add3_u32 v246, s2, v6, 3
	v_mad_i64_i32 v[246:247], s[10:11], v246, s58, v[2:3]
	global_load_dword v230, v[246:247], off
	v_add3_u32 v246, s2, v6, 4
	v_mad_i64_i32 v[246:247], s[10:11], v246, s58, v[2:3]
	global_load_dword v231, v[246:247], off
	v_add3_u32 v246, s2, v6, 5
	v_mad_i64_i32 v[246:247], s[10:11], v246, s58, v[2:3]
	global_load_dword v232, v[246:247], off
	v_add3_u32 v246, s2, v6, 6
	v_mad_i64_i32 v[246:247], s[10:11], v246, s58, v[2:3]
	global_load_dword v233, v[246:247], off
	v_add3_u32 v246, s2, v6, 7
	v_mad_i64_i32 v[246:247], s[10:11], v246, s58, v[2:3]
	global_load_dword v234, v[246:247], off
	v_add3_u32 v246, s2, v6, 8
	v_mad_i64_i32 v[246:247], s[10:11], v246, s58, v[2:3]
	global_load_dword v235, v[246:247], off
	v_add3_u32 v246, s2, v6, 9
	v_mad_i64_i32 v[246:247], s[10:11], v246, s58, v[2:3]
	global_load_dword v236, v[246:247], off
	v_add3_u32 v246, s2, v6, 10
	v_mad_i64_i32 v[246:247], s[10:11], v246, s58, v[2:3]
	global_load_dword v237, v[246:247], off
	v_add3_u32 v246, s2, v6, 11
	v_mad_i64_i32 v[246:247], s[10:11], v246, s58, v[2:3]
	global_load_dword v238, v[246:247], off
	v_add3_u32 v246, s2, v6, 12
	v_mad_i64_i32 v[246:247], s[10:11], v246, s58, v[2:3]
	global_load_dword v239, v[246:247], off
	v_add3_u32 v246, s2, v6, 13
	v_mad_i64_i32 v[246:247], s[10:11], v246, s58, v[2:3]
	global_load_dword v240, v[246:247], off
.Lbt_1:
	s_or_b64 exec, exec, s[0:1]
	s_waitcnt vmcnt(12)
	ds_write_b32 v7, v228 offset:260
	s_waitcnt vmcnt(11)
	ds_write_b32 v7, v229 offset:520
	s_waitcnt vmcnt(10)
	ds_write_b32 v7, v230 offset:780
	s_waitcnt vmcnt(9)
	ds_write_b32 v7, v231 offset:1040
	s_waitcnt vmcnt(8)
	ds_write_b32 v7, v232 offset:1300
	s_waitcnt vmcnt(7)
	ds_write_b32 v7, v233 offset:1560
	s_waitcnt vmcnt(6)
	ds_write_b32 v7, v234 offset:1820
	s_waitcnt vmcnt(5)
	ds_write_b32 v7, v235 offset:2080
	s_waitcnt vmcnt(4)
	ds_write_b32 v7, v236 offset:2340
	s_waitcnt vmcnt(3)
	ds_write_b32 v7, v237 offset:2600
	s_waitcnt vmcnt(2)
	ds_write_b32 v7, v238 offset:2860
	s_waitcnt vmcnt(1)
	ds_write_b32 v7, v239 offset:3120
	s_waitcnt vmcnt(0)
	ds_write_b32 v7, v240 offset:3380
	v_mov_b32_e32 v8, 0
	v_mov_b32_e32 v9, 0
	v_mov_b32_e32 v8, 0
	v_mov_b32_e32 v9, 0
	s_and_saveexec_b64 s[0:1], vcc
	s_cbranch_execz .LBB0_98
	v_add3_u32 v6, s2, v6, 14
	v_mad_i64_i32 v[10:11], s[10:11], v6, s58, v[2:3]
	global_load_dword v9, v[10:11], off

; DI void transpose_tile(const float* __restrict__ src, int sld, int k0, int n0, int kind, u16* __restrict__ dst, int dld,
;                        char* ldsraw) {
;     ...
; #pragma unroll
;     for (int i = 0; i < 16; ++i) {
;       const int kk = kq * 16 + i;
;       t[kk * 65 + nn] = (sc >= 0) ? src[(size_t)(k0 + kk) * sld + sc] : 0.f;
;     }
.LBB0_145:
	s_or_b64 exec, exec, s[0:1]
	v_and_b32_e32 v0, 63, v4
	v_lshlrev_b32_e32 v0, 2, v0
	v_mul_lo_u32 v7, v6, s57
	v_add_u32_e32 v7, v0, v7
	s_waitcnt vmcnt(0)
	ds_write_b32 v7, v9
	v_mov_b32_e32 v228, 0
	v_mov_b32_e32 v229, 0
	v_mov_b32_e32 v230, 0
	v_mov_b32_e32 v231, 0
	v_mov_b32_e32 v232, 0
	v_mov_b32_e32 v233, 0
	v_mov_b32_e32 v234, 0
	v_mov_b32_e32 v235, 0
	v_mov_b32_e32 v236, 0
	v_mov_b32_e32 v237, 0
	v_mov_b32_e32 v238, 0
	v_mov_b32_e32 v239, 0
	v_mov_b32_e32 v240, 0
	s_and_saveexec_b64 s[0:1], vcc
	s_cbranch_execz .Lbt_2
	v_add3_u32 v246, s2, v6, 1
	v_mad_i64_i32 v[246:247], s[8:9], v246, s58, v[2:3]
	global_load_dword v228, v[246:247], off
	v_add3_u32 v246, s2, v6, 2
	v_mad_i64_i32 v[246:247], s[8:9], v246, s58, v[2:3]
	global_load_dword v229, v[246:247], off
	v_add3_u32 v246, s2, v6, 3
	v_mad_i64_i32 v[246:247], s[8:9], v246, s58, v[2:3]
	global_load_dword v230, v[246:247], off
	v_add3_u32 v246, s2, v6, 4
	v_mad_i64_i32 v[246:247], s[8:9], v246, s58, v[2:3]
	global_load_dword v231, v[246:247], off
	v_add3_u32 v246, s2, v6, 5
	v_mad_i64_i32 v[246:247], s[8:9], v246, s58, v[2:3]
	global_load_dword v232, v[246:247], off
	v_add3_u32 v246, s2, v6, 6
	v_mad_i64_i32 v[246:247], s[8:9], v246, s58, v[2:3]
	global_load_dword v233, v[246:247], off
	v_add3_u32 v246, s2, v6, 7
	v_mad_i64_i32 v[246:247], s[8:9], v246, s58, v[2:3]
	global_load_dword v234, v[246:247], off
	v_add3_u32 v246, s2, v6, 8
	v_mad_i64_i32 v[246:247], s[8:9], v246, s58, v[2:3]
	global_load_dword v235, v[246:247], off
	v_add3_u32 v246, s2, v6, 9
	v_mad_i64_i32 v[246:247], s[8:9], v246, s58, v[2:3]
	global_load_dword v236, v[246:247], off
	v_add3_u32 v246, s2, v6, 10
	v_mad_i64_i32 v[246:247], s[8:9], v246, s58, v[2:3]
	global_load_dword v237, v[246:247], off
	v_add3_u32 v246, s2, v6, 11
	v_mad_i64_i32 v[246:247], s[8:9], v246, s58, v[2:3]
	global_load_dword v238, v[246:247], off
	v_add3_u32 v246, s2, v6, 12
	v_mad_i64_i32 v[246:247], s[8:9], v246, s58, v[2:3]
	global_load_dword v239, v[246:247], off
	v_add3_u32 v246, s2, v6, 13
	v_mad_i64_i32 v[246:247], s[8:9], v246, s58, v[2:3]
	global_load_dword v240, v[246:247], off
.Lbt_2:
	s_or_b64 exec, exec, s[0:1]
	s_waitcnt vmcnt(12)
	ds_write_b32 v7, v228 offset:260
	s_waitcnt vmcnt(11)
	ds_write_b32 v7, v229 offset:520
	s_waitcnt vmcnt(10)
	ds_write_b32 v7, v230 offset:780
	s_waitcnt vmcnt(9)
	ds_write_b32 v7, v231 offset:1040
	s_waitcnt vmcnt(8)
	ds_write_b32 v7, v232 offset:1300
	s_waitcnt vmcnt(7)
	ds_write_b32 v7, v233 offset:1560
	s_waitcnt vmcnt(6)
	ds_write_b32 v7, v234 offset:1820
	s_waitcnt vmcnt(5)
	ds_write_b32 v7, v235 offset:2080
	s_waitcnt vmcnt(4)
	ds_write_b32 v7, v236 offset:2340
	s_waitcnt vmcnt(3)
	ds_write_b32 v7, v237 offset:2600
	s_waitcnt vmcnt(2)
	ds_write_b32 v7, v238 offset:2860
	s_waitcnt vmcnt(1)
	ds_write_b32 v7, v239 offset:3120
	s_waitcnt vmcnt(0)
	ds_write_b32 v7, v240 offset:3380
	v_mov_b32_e32 v8, 0
	v_mov_b32_e32 v9, 0
	v_mov_b32_e32 v8, 0
	v_mov_b32_e32 v9, 0
	s_and_saveexec_b64 s[0:1], vcc
	s_cbranch_execz .LBB0_173
	v_add3_u32 v6, s2, v6, 14
	v_mad_i64_i32 v[10:11], s[8:9], v6, s58, v[2:3]
	global_load_dword v9, v[10:11], off

; DI void transpose_tile(const float* __restrict__ src, int sld, int k0, int n0, int kind, u16* __restrict__ dst, int dld,
;                        char* ldsraw) {
;     ...
; #pragma unroll
;     for (int i = 0; i < 16; ++i) {
;       const int kk = kq * 16 + i;
;       t[kk * 65 + nn] = (sc >= 0) ? src[(size_t)(k0 + kk) * sld + sc] : 0.f;
;     }
.LBB0_557:
	s_or_b64 exec, exec, s[0:1]
	v_and_b32_e32 v0, 63, v4
	v_lshlrev_b32_e32 v0, 2, v0
	v_mul_lo_u32 v7, v6, s57
	v_add_u32_e32 v7, v0, v7
	s_waitcnt vmcnt(0)
	ds_write_b32 v7, v9
	v_mov_b32_e32 v228, 0
	v_mov_b32_e32 v229, 0
	v_mov_b32_e32 v230, 0
	v_mov_b32_e32 v231, 0
	v_mov_b32_e32 v232, 0
	v_mov_b32_e32 v233, 0
	v_mov_b32_e32 v234, 0
	v_mov_b32_e32 v235, 0
	v_mov_b32_e32 v236, 0
	v_mov_b32_e32 v237, 0
	v_mov_b32_e32 v238, 0
	v_mov_b32_e32 v239, 0
	v_mov_b32_e32 v240, 0
	s_and_saveexec_b64 s[0:1], vcc
	s_cbranch_execz .Lbt_3
	v_add3_u32 v246, s2, v6, 1
	v_mad_i64_i32 v[246:247], s[6:7], v246, s58, v[2:3]
	global_load_dword v228, v[246:247], off
	v_add3_u32 v246, s2, v6, 2
	v_mad_i64_i32 v[246:247], s[6:7], v246, s58, v[2:3]
	global_load_dword v229, v[246:247], off
	v_add3_u32 v246, s2, v6, 3
	v_mad_i64_i32 v[246:247], s[6:7], v246, s58, v[2:3]
	global_load_dword v230, v[246:247], off
	v_add3_u32 v246, s2, v6, 4
	v_mad_i64_i32 v[246:247], s[6:7], v246, s58, v[2:3]
	global_load_dword v231, v[246:247], off
	v_add3_u32 v246, s2, v6, 5
	v_mad_i64_i32 v[246:247], s[6:7], v246, s58, v[2:3]
	global_load_dword v232, v[246:247], off
	v_add3_u32 v246, s2, v6, 6
	v_mad_i64_i32 v[246:247], s[6:7], v246, s58, v[2:3]
	global_load_dword v233, v[246:247], off
	v_add3_u32 v246, s2, v6, 7
	v_mad_i64_i32 v[246:247], s[6:7], v246, s58, v[2:3]
	global_load_dword v234, v[246:247], off
	v_add3_u32 v246, s2, v6, 8
	v_mad_i64_i32 v[246:247], s[6:7], v246, s58, v[2:3]
	global_load_dword v235, v[246:247], off
	v_add3_u32 v246, s2, v6, 9
	v_mad_i64_i32 v[246:247], s[6:7], v246, s58, v[2:3]
	global_load_dword v236, v[246:247], off
	v_add3_u32 v246, s2, v6, 10
	v_mad_i64_i32 v[246:247], s[6:7], v246, s58, v[2:3]
	global_load_dword v237, v[246:247], off
	v_add3_u32 v246, s2, v6, 11
	v_mad_i64_i32 v[246:247], s[6:7], v246, s58, v[2:3]
	global_load_dword v238, v[246:247], off
	v_add3_u32 v246, s2, v6, 12
	v_mad_i64_i32 v[246:247], s[6:7], v246, s58, v[2:3]
	global_load_dword v239, v[246:247], off
	v_add3_u32 v246, s2, v6, 13
	v_mad_i64_i32 v[246:247], s[6:7], v246, s58, v[2:3]
	global_load_dword v240, v[246:247], off
.Lbt_3:
	s_or_b64 exec, exec, s[0:1]
	s_waitcnt vmcnt(12)
	ds_write_b32 v7, v228 offset:260
	s_waitcnt vmcnt(11)
	ds_write_b32 v7, v229 offset:520
	s_waitcnt vmcnt(10)
	ds_write_b32 v7, v230 offset:780
	s_waitcnt vmcnt(9)
	ds_write_b32 v7, v231 offset:1040
	s_waitcnt vmcnt(8)
	ds_write_b32 v7, v232 offset:1300
	s_waitcnt vmcnt(7)
	ds_write_b32 v7, v233 offset:1560
	s_waitcnt vmcnt(6)
	ds_write_b32 v7, v234 offset:1820
	s_waitcnt vmcnt(5)
	ds_write_b32 v7, v235 offset:2080
	s_waitcnt vmcnt(4)
	ds_write_b32 v7, v236 offset:2340
	s_waitcnt vmcnt(3)
	ds_write_b32 v7, v237 offset:2600
	s_waitcnt vmcnt(2)
	ds_write_b32 v7, v238 offset:2860
	s_waitcnt vmcnt(1)
	ds_write_b32 v7, v239 offset:3120
	s_waitcnt vmcnt(0)
	ds_write_b32 v7, v240 offset:3380
	v_mov_b32_e32 v8, 0
	v_mov_b32_e32 v9, 0
	v_mov_b32_e32 v8, 0
	v_mov_b32_e32 v9, 0
	s_and_saveexec_b64 s[0:1], vcc
	s_cbranch_execz .LBB0_585
	v_add3_u32 v6, s2, v6, 14
	v_mad_i64_i32 v[10:11], s[6:7], v6, s58, v[2:3]
	global_load_dword v9, v[10:11], off
